# phase 0 rms_rows: four rows per loop trip (16 loads in flight per wave, interleaved reductions); one-row loop kept for a remainder
# speedup vs baseline: 1.0034x; 1.0034x over previous
.Lrms4_chk:
	s_mul_i32 s10, s98, 3
	s_add_i32 s10, s10, s0
	s_cmpk_gt_i32 s10, 0x7fff
	s_cbranch_scc1 .Lrms4_done
	v_lshl_add_u64 v[112:113], v[20:21], 0, s[8:9]
	v_lshl_add_u64 v[114:115], v[112:113], 0, s[8:9]
	v_lshl_add_u64 v[116:117], v[114:115], 0, s[8:9]
	global_load_dwordx4 v[28:31], v[20:21], off offset:-3072 nt
	global_load_dwordx4 v[32:35], v[20:21], off offset:-2048 nt
	global_load_dwordx4 v[36:39], v[20:21], off offset:-1024 nt
	global_load_dwordx4 v[40:43], v[20:21], off nt
	global_load_dwordx4 v[60:63], v[112:113], off offset:-3072 nt
	global_load_dwordx4 v[64:67], v[112:113], off offset:-2048 nt
	global_load_dwordx4 v[68:71], v[112:113], off offset:-1024 nt
	global_load_dwordx4 v[72:75], v[112:113], off nt
	global_load_dwordx4 v[76:79], v[114:115], off offset:-3072 nt
	global_load_dwordx4 v[80:83], v[114:115], off offset:-2048 nt
	global_load_dwordx4 v[84:87], v[114:115], off offset:-1024 nt
	global_load_dwordx4 v[88:91], v[114:115], off nt
	global_load_dwordx4 v[92:95], v[116:117], off offset:-3072 nt
	global_load_dwordx4 v[96:99], v[116:117], off offset:-2048 nt
	global_load_dwordx4 v[100:103], v[116:117], off offset:-1024 nt
	global_load_dwordx4 v[104:107], v[116:117], off nt
	v_lshl_add_u64 v[118:119], v[18:19], 0, s[6:7]
	v_lshl_add_u64 v[120:121], v[118:119], 0, s[6:7]
	v_lshl_add_u64 v[122:123], v[120:121], 0, s[6:7]
	s_waitcnt vmcnt(12)
	v_pk_mul_f32 v[44:45], v[28:29], v[28:29]
	v_pk_fma_f32 v[44:45], v[30:31], v[30:31], v[44:45]
	v_pk_fma_f32 v[44:45], v[32:33], v[32:33], v[44:45]
	v_pk_fma_f32 v[44:45], v[34:35], v[34:35], v[44:45]
	v_pk_fma_f32 v[44:45], v[36:37], v[36:37], v[44:45]
	v_pk_fma_f32 v[44:45], v[38:39], v[38:39], v[44:45]
	v_pk_fma_f32 v[44:45], v[40:41], v[40:41], v[44:45]
	v_pk_fma_f32 v[44:45], v[42:43], v[42:43], v[44:45]
	s_waitcnt vmcnt(8)
	v_pk_mul_f32 v[46:47], v[60:61], v[60:61]
	v_pk_fma_f32 v[46:47], v[62:63], v[62:63], v[46:47]
	v_pk_fma_f32 v[46:47], v[64:65], v[64:65], v[46:47]
	v_pk_fma_f32 v[46:47], v[66:67], v[66:67], v[46:47]
	v_pk_fma_f32 v[46:47], v[68:69], v[68:69], v[46:47]
	v_pk_fma_f32 v[46:47], v[70:71], v[70:71], v[46:47]
	v_pk_fma_f32 v[46:47], v[72:73], v[72:73], v[46:47]
	v_pk_fma_f32 v[46:47], v[74:75], v[74:75], v[46:47]
	s_waitcnt vmcnt(4)
	v_pk_mul_f32 v[48:49], v[76:77], v[76:77]
	v_pk_fma_f32 v[48:49], v[78:79], v[78:79], v[48:49]
	v_pk_fma_f32 v[48:49], v[80:81], v[80:81], v[48:49]
	v_pk_fma_f32 v[48:49], v[82:83], v[82:83], v[48:49]
	v_pk_fma_f32 v[48:49], v[84:85], v[84:85], v[48:49]
	v_pk_fma_f32 v[48:49], v[86:87], v[86:87], v[48:49]
	v_pk_fma_f32 v[48:49], v[88:89], v[88:89], v[48:49]
	v_pk_fma_f32 v[48:49], v[90:91], v[90:91], v[48:49]
	s_waitcnt vmcnt(0)
	v_pk_mul_f32 v[50:51], v[92:93], v[92:93]
	v_pk_fma_f32 v[50:51], v[94:95], v[94:95], v[50:51]
	v_pk_fma_f32 v[50:51], v[96:97], v[96:97], v[50:51]
	v_pk_fma_f32 v[50:51], v[98:99], v[98:99], v[50:51]
	v_pk_fma_f32 v[50:51], v[100:101], v[100:101], v[50:51]
	v_pk_fma_f32 v[50:51], v[102:103], v[102:103], v[50:51]
	v_pk_fma_f32 v[50:51], v[104:105], v[104:105], v[50:51]
	v_pk_fma_f32 v[50:51], v[106:107], v[106:107], v[50:51]
	v_add_f32_e32 v44, v44, v45
	v_add_f32_e32 v46, v46, v47
	v_add_f32_e32 v48, v48, v49
	v_add_f32_e32 v50, v50, v51
	ds_bpermute_b32 v52, v0, v44
	ds_bpermute_b32 v53, v0, v46
	ds_bpermute_b32 v54, v0, v48
	ds_bpermute_b32 v55, v0, v50
	s_waitcnt lgkmcnt(0)
	v_add_f32_e32 v44, v44, v52
	v_add_f32_e32 v46, v46, v53
	v_add_f32_e32 v48, v48, v54
	v_add_f32_e32 v50, v50, v55
	ds_bpermute_b32 v52, v22, v44
	ds_bpermute_b32 v53, v22, v46
	ds_bpermute_b32 v54, v22, v48
	ds_bpermute_b32 v55, v22, v50
	s_waitcnt lgkmcnt(0)
	v_add_f32_e32 v44, v44, v52
	v_add_f32_e32 v46, v46, v53
	v_add_f32_e32 v48, v48, v54
	v_add_f32_e32 v50, v50, v55
	ds_bpermute_b32 v52, v23, v44
	ds_bpermute_b32 v53, v23, v46
	ds_bpermute_b32 v54, v23, v48
	ds_bpermute_b32 v55, v23, v50
	s_waitcnt lgkmcnt(0)
	v_add_f32_e32 v44, v44, v52
	v_add_f32_e32 v46, v46, v53
	v_add_f32_e32 v48, v48, v54
	v_add_f32_e32 v50, v50, v55
	ds_bpermute_b32 v52, v24, v44
	ds_bpermute_b32 v53, v24, v46
	ds_bpermute_b32 v54, v24, v48
	ds_bpermute_b32 v55, v24, v50
	s_waitcnt lgkmcnt(0)
	v_add_f32_e32 v44, v44, v52
	v_add_f32_e32 v46, v46, v53
	v_add_f32_e32 v48, v48, v54
	v_add_f32_e32 v50, v50, v55
	ds_bpermute_b32 v52, v25, v44
	ds_bpermute_b32 v53, v25, v46
	ds_bpermute_b32 v54, v25, v48
	ds_bpermute_b32 v55, v25, v50
	s_waitcnt lgkmcnt(0)
	v_add_f32_e32 v44, v44, v52
	v_add_f32_e32 v46, v46, v53
	v_add_f32_e32 v48, v48, v54
	v_add_f32_e32 v50, v50, v55
	ds_bpermute_b32 v52, v26, v44
	ds_bpermute_b32 v53, v26, v46
	ds_bpermute_b32 v54, v26, v48
	ds_bpermute_b32 v55, v26, v50
	s_waitcnt lgkmcnt(0)
	v_add_f32_e32 v44, v44, v52
	v_add_f32_e32 v46, v46, v53
	v_add_f32_e32 v48, v48, v54
	v_add_f32_e32 v50, v50, v55
	v_fmamk_f32 v44, v44, 0x3a800000, v205
	v_fmamk_f32 v46, v46, 0x3a800000, v205
	v_fmamk_f32 v48, v48, 0x3a800000, v205
	v_fmamk_f32 v50, v50, 0x3a800000, v205
	v_mul_f32_e32 v52, 0x4b800000, v44
	v_cmp_gt_f32_e32 vcc, s83, v44
	s_nop 1
	v_cndmask_b32_e32 v44, v44, v52, vcc
	v_rsq_f32_e32 v44, v44
	s_nop 0
	v_mul_f32_e32 v52, 0x45800000, v44
	v_cndmask_b32_e32 v56, v44, v52, vcc
	v_mul_f32_e32 v53, 0x4b800000, v46
	v_cmp_gt_f32_e32 vcc, s83, v46
	s_nop 1
	v_cndmask_b32_e32 v46, v46, v53, vcc
	v_rsq_f32_e32 v46, v46
	s_nop 0
	v_mul_f32_e32 v53, 0x45800000, v46
	v_cndmask_b32_e32 v58, v46, v53, vcc
	v_mul_f32_e32 v54, 0x4b800000, v48
	v_cmp_gt_f32_e32 vcc, s83, v48
	s_nop 1
	v_cndmask_b32_e32 v48, v48, v54, vcc
	v_rsq_f32_e32 v48, v48
	s_nop 0
	v_mul_f32_e32 v54, 0x45800000, v48
	v_cndmask_b32_e32 v108, v48, v54, vcc
	v_mul_f32_e32 v55, 0x4b800000, v50
	v_cmp_gt_f32_e32 vcc, s83, v50
	s_nop 1
	v_cndmask_b32_e32 v50, v50, v55, vcc
	v_rsq_f32_e32 v50, v50
	s_nop 0
	v_mul_f32_e32 v55, 0x45800000, v50
	v_cndmask_b32_e32 v110, v50, v55, vcc
	v_pk_mul_f32 v[28:29], v[28:29], v[56:57] op_sel_hi:[1,0]
	v_pk_mul_f32 v[30:31], v[30:31], v[56:57] op_sel_hi:[1,0]
	v_pk_mul_f32 v[32:33], v[32:33], v[56:57] op_sel_hi:[1,0]
	v_pk_mul_f32 v[34:35], v[34:35], v[56:57] op_sel_hi:[1,0]
	v_pk_mul_f32 v[36:37], v[36:37], v[56:57] op_sel_hi:[1,0]
	v_pk_mul_f32 v[38:39], v[38:39], v[56:57] op_sel_hi:[1,0]
	v_pk_mul_f32 v[40:41], v[40:41], v[56:57] op_sel_hi:[1,0]
	v_pk_mul_f32 v[42:43], v[42:43], v[56:57] op_sel_hi:[1,0]
	v_pk_mul_f32 v[28:29], v[14:15], v[28:29]
	v_pk_mul_f32 v[30:31], v[16:17], v[30:31]
	v_pk_mul_f32 v[32:33], v[10:11], v[32:33]
	v_pk_mul_f32 v[34:35], v[12:13], v[34:35]
	v_pk_mul_f32 v[36:37], v[6:7], v[36:37]
	v_pk_mul_f32 v[38:39], v[8:9], v[38:39]
	v_pk_mul_f32 v[40:41], v[2:3], v[40:41]
	v_pk_mul_f32 v[42:43], v[4:5], v[42:43]
	v_cvt_pk_bf16_f32 v28, v28, v29
	v_cvt_pk_bf16_f32 v29, v30, v31
	v_cvt_pk_bf16_f32 v30, v32, v33
	v_cvt_pk_bf16_f32 v31, v34, v35
	v_cvt_pk_bf16_f32 v32, v36, v37
	v_cvt_pk_bf16_f32 v33, v38, v39
	v_cvt_pk_bf16_f32 v34, v40, v41
	v_cvt_pk_bf16_f32 v35, v42, v43
	global_store_dwordx2 v[18:19], v[28:29], off
	global_store_dwordx2 v[18:19], v[30:31], off offset:512
	global_store_dwordx2 v[18:19], v[32:33], off offset:1024
	global_store_dwordx2 v[18:19], v[34:35], off offset:1536
	v_pk_mul_f32 v[60:61], v[60:61], v[58:59] op_sel_hi:[1,0]
	v_pk_mul_f32 v[62:63], v[62:63], v[58:59] op_sel_hi:[1,0]
	v_pk_mul_f32 v[64:65], v[64:65], v[58:59] op_sel_hi:[1,0]
	v_pk_mul_f32 v[66:67], v[66:67], v[58:59] op_sel_hi:[1,0]
	v_pk_mul_f32 v[68:69], v[68:69], v[58:59] op_sel_hi:[1,0]
	v_pk_mul_f32 v[70:71], v[70:71], v[58:59] op_sel_hi:[1,0]
	v_pk_mul_f32 v[72:73], v[72:73], v[58:59] op_sel_hi:[1,0]
	v_pk_mul_f32 v[74:75], v[74:75], v[58:59] op_sel_hi:[1,0]
	v_pk_mul_f32 v[60:61], v[14:15], v[60:61]
	v_pk_mul_f32 v[62:63], v[16:17], v[62:63]
	v_pk_mul_f32 v[64:65], v[10:11], v[64:65]
	v_pk_mul_f32 v[66:67], v[12:13], v[66:67]
	v_pk_mul_f32 v[68:69], v[6:7], v[68:69]
	v_pk_mul_f32 v[70:71], v[8:9], v[70:71]
	v_pk_mul_f32 v[72:73], v[2:3], v[72:73]
	v_pk_mul_f32 v[74:75], v[4:5], v[74:75]
	v_cvt_pk_bf16_f32 v60, v60, v61
	v_cvt_pk_bf16_f32 v61, v62, v63
	v_cvt_pk_bf16_f32 v62, v64, v65
	v_cvt_pk_bf16_f32 v63, v66, v67
	v_cvt_pk_bf16_f32 v64, v68, v69
	v_cvt_pk_bf16_f32 v65, v70, v71
	v_cvt_pk_bf16_f32 v66, v72, v73
	v_cvt_pk_bf16_f32 v67, v74, v75
	global_store_dwordx2 v[118:119], v[60:61], off
	global_store_dwordx2 v[118:119], v[62:63], off offset:512
	global_store_dwordx2 v[118:119], v[64:65], off offset:1024
	global_store_dwordx2 v[118:119], v[66:67], off offset:1536
	v_pk_mul_f32 v[76:77], v[76:77], v[108:109] op_sel_hi:[1,0]
	v_pk_mul_f32 v[78:79], v[78:79], v[108:109] op_sel_hi:[1,0]
	v_pk_mul_f32 v[80:81], v[80:81], v[108:109] op_sel_hi:[1,0]
	v_pk_mul_f32 v[82:83], v[82:83], v[108:109] op_sel_hi:[1,0]
	v_pk_mul_f32 v[84:85], v[84:85], v[108:109] op_sel_hi:[1,0]
	v_pk_mul_f32 v[86:87], v[86:87], v[108:109] op_sel_hi:[1,0]
	v_pk_mul_f32 v[88:89], v[88:89], v[108:109] op_sel_hi:[1,0]
	v_pk_mul_f32 v[90:91], v[90:91], v[108:109] op_sel_hi:[1,0]
	v_pk_mul_f32 v[76:77], v[14:15], v[76:77]
	v_pk_mul_f32 v[78:79], v[16:17], v[78:79]
	v_pk_mul_f32 v[80:81], v[10:11], v[80:81]
	v_pk_mul_f32 v[82:83], v[12:13], v[82:83]
	v_pk_mul_f32 v[84:85], v[6:7], v[84:85]
	v_pk_mul_f32 v[86:87], v[8:9], v[86:87]
	v_pk_mul_f32 v[88:89], v[2:3], v[88:89]
	v_pk_mul_f32 v[90:91], v[4:5], v[90:91]
	v_cvt_pk_bf16_f32 v76, v76, v77
	v_cvt_pk_bf16_f32 v77, v78, v79
	v_cvt_pk_bf16_f32 v78, v80, v81
	v_cvt_pk_bf16_f32 v79, v82, v83
	v_cvt_pk_bf16_f32 v80, v84, v85
	v_cvt_pk_bf16_f32 v81, v86, v87
	v_cvt_pk_bf16_f32 v82, v88, v89
	v_cvt_pk_bf16_f32 v83, v90, v91
	global_store_dwordx2 v[120:121], v[76:77], off
	global_store_dwordx2 v[120:121], v[78:79], off offset:512
	global_store_dwordx2 v[120:121], v[80:81], off offset:1024
	global_store_dwordx2 v[120:121], v[82:83], off offset:1536
	v_pk_mul_f32 v[92:93], v[92:93], v[110:111] op_sel_hi:[1,0]
	v_pk_mul_f32 v[94:95], v[94:95], v[110:111] op_sel_hi:[1,0]
	v_pk_mul_f32 v[96:97], v[96:97], v[110:111] op_sel_hi:[1,0]
	v_pk_mul_f32 v[98:99], v[98:99], v[110:111] op_sel_hi:[1,0]
	v_pk_mul_f32 v[100:101], v[100:101], v[110:111] op_sel_hi:[1,0]
	v_pk_mul_f32 v[102:103], v[102:103], v[110:111] op_sel_hi:[1,0]
	v_pk_mul_f32 v[104:105], v[104:105], v[110:111] op_sel_hi:[1,0]
	v_pk_mul_f32 v[106:107], v[106:107], v[110:111] op_sel_hi:[1,0]
	v_pk_mul_f32 v[92:93], v[14:15], v[92:93]
	v_pk_mul_f32 v[94:95], v[16:17], v[94:95]
	v_pk_mul_f32 v[96:97], v[10:11], v[96:97]
	v_pk_mul_f32 v[98:99], v[12:13], v[98:99]
	v_pk_mul_f32 v[100:101], v[6:7], v[100:101]
	v_pk_mul_f32 v[102:103], v[8:9], v[102:103]
	v_pk_mul_f32 v[104:105], v[2:3], v[104:105]
	v_pk_mul_f32 v[106:107], v[4:5], v[106:107]
	v_cvt_pk_bf16_f32 v92, v92, v93
	v_cvt_pk_bf16_f32 v93, v94, v95
	v_cvt_pk_bf16_f32 v94, v96, v97
	v_cvt_pk_bf16_f32 v95, v98, v99
	v_cvt_pk_bf16_f32 v96, v100, v101
	v_cvt_pk_bf16_f32 v97, v102, v103
	v_cvt_pk_bf16_f32 v98, v104, v105
	v_cvt_pk_bf16_f32 v99, v106, v107
	global_store_dwordx2 v[122:123], v[92:93], off
	global_store_dwordx2 v[122:123], v[94:95], off offset:512
	global_store_dwordx2 v[122:123], v[96:97], off offset:1024
	global_store_dwordx2 v[122:123], v[98:99], off offset:1536
	s_lshl_b64 s[12:13], s[8:9], 2
	s_lshl_b64 s[14:15], s[6:7], 2
	s_lshl_b32 s16, s98, 2
	v_lshl_add_u64 v[20:21], v[20:21], 0, s[12:13]
	v_lshl_add_u64 v[18:19], v[18:19], 0, s[14:15]
	s_add_i32 s0, s0, s16
	s_branch .Lrms4_chk
.Lrms4_done:
	s_cmpk_gt_i32 s0, 0x7fff
	s_cbranch_scc1 .LBB0_731
